# attention: removed loop-carried vmcnt waits in QK phase (Q fragments waited once per unit), next-tile bias load consumed at the tile-write point instead of vmcnt(0) at the top
# speedup vs baseline: 1.0094x; 1.0094x over previous
; #define AT_LOAD(t) do { \
;     _Pragma("unroll") for (int i_ = 0; i_ < 4; ++i_) { rk[i_] = *(const u32x4*)(kg + (size_t)((t) * 128 + 32 * i_) * 3072); rv[i_] = *(const u32x4*)(vg + (size_t)(16 * i_) * SEQ + (t) * 128); } \
;     if (gt < 128) { const int j_ = (t) * 128 + gt; rbias = (fend - fl[j_] + suf[j_ >> 7]) * LOG2E; } } while (0)
; #define AT_STORE(st) do { \
;     _Pragma("unroll") for (int i_ = 0; i_ < 4; ++i_) { *(u32x4*)(smem + (st) + AT_K + sk_ + 32 * i_ * LROW) = rk[i_]; *(u32x4*)(smem + (st) + AT_V + sv_ + 16 * i_ * VROW) = rv[i_]; } \
;     if (gt < 128) *(float*)(smem + (st) + AT_BIAS + gt * 4) = rbias; } while (0)
; DEV void attn_unit(const Params& P, int b, int qb, int h) {
;     ...
;   const int niter = (NT2 - ts2 + 1) >> 1;
;   if (ts2 + g < NT2) { AT_LOAD(ts2 + g); AT_STORE(gbase); }
;   __syncthreads();
;   float m = -INFINITY, l = 0.f;
;   f32x16 o[2];
; #pragma unroll
;   for (int r = 0; r < 16; ++r) { o[0][r] = 0.f; o[1][r] = 0.f; }
.LBB0_174:
	s_or_b64 exec, exec, s[8:9]
	s_add_i32 s24, s24, s12
	s_sub_i32 s8, 0x81, s24
	s_ashr_i32 s41, s8, 1
	v_lshlrev_b32_e32 v118, 3, v2
	s_cmp_lt_i32 s41, 1
	s_waitcnt lgkmcnt(0)
	s_barrier
	s_cbranch_scc1 .LBB0_192
	s_waitcnt vmcnt(0)
	s_or_b32 s42, s2, 1
	v_cmp_lt_u32_e64 s[8:9], 1, v130
	v_or_b32_e32 v140, v3, v133
	v_lshlrev_b32_e32 v141, 2, v2
	v_add_u32_e32 v142, 0, v4
	v_lshlrev_b32_e32 v143, 2, v131
	v_mul_u32_u24_e32 v144, 0x110, v133
	s_mov_b32 s43, 0
	v_mov_b32_e32 v16, v113
	v_mov_b32_e32 v17, v113
	v_mov_b32_e32 v18, v113
	v_mov_b32_e32 v19, v113
	v_mov_b32_e32 v20, v113
	v_mov_b32_e32 v21, v113
	v_mov_b32_e32 v22, v113
	v_mov_b32_e32 v23, v113
	v_mov_b32_e32 v24, v113
	v_mov_b32_e32 v25, v113
	v_mov_b32_e32 v26, v113
	v_mov_b32_e32 v27, v113
	v_mov_b32_e32 v28, v113
	v_mov_b32_e32 v29, v113
	v_mov_b32_e32 v30, v113
	v_mov_b32_e32 v31, v113
	v_mov_b32_e32 v0, v113
	v_mov_b32_e32 v1, v113
	v_mov_b32_e32 v2, v113
	v_mov_b32_e32 v3, v113
	v_mov_b32_e32 v4, v113
	v_mov_b32_e32 v5, v113
	v_mov_b32_e32 v6, v113
	v_mov_b32_e32 v7, v113
	v_mov_b32_e32 v8, v113
	v_mov_b32_e32 v9, v113
	v_mov_b32_e32 v10, v113
	v_mov_b32_e32 v11, v113
	v_mov_b32_e32 v12, v113
	v_mov_b32_e32 v13, v113
	v_mov_b32_e32 v14, v113
	v_mov_b32_e32 v15, v113
	v_mov_b32_e32 v125, 0xff800000
	v_mov_b32_e32 v124, 0
	s_branch .LBB0_177

; #define AT_LOAD(t) do { \
;     _Pragma("unroll") for (int i_ = 0; i_ < 4; ++i_) { rk[i_] = *(const u32x4*)(kg + (size_t)((t) * 128 + 32 * i_) * 3072); rv[i_] = *(const u32x4*)(vg + (size_t)(16 * i_) * SEQ + (t) * 128); } \
;     if (gt < 128) { const int j_ = (t) * 128 + gt; rbias = (fend - fl[j_] + suf[j_ >> 7]) * LOG2E; } } while (0)
; DEV void attn_unit(const Params& P, int b, int qb, int h) {
;     ...
;   for (int it = 0; it < niter; ++it) {
;     const int t2 = ts2 + 2 * it + g;
;     const int st = gbase + (it & 1) * AT_STG;
;     const bool more = t2 + 2 < NT2;
;     if (more) AT_LOAD(t2 + 2);
.LBB0_177:
	v_lshl_add_u32 v34, s43, 1, v138
	v_add_u32_e32 v32, 2, v34
	v_cmp_ge_i32_e64 s[10:11], s40, v32
	s_and_saveexec_b64 s[12:13], s[10:11]
	s_cbranch_execz .LBB0_181
	v_lshlrev_b32_e32 v32, 7, v32
	v_ashrrev_i32_e32 v33, 31, v32
	v_lshl_add_u64 v[36:37], v[32:33], 1, v[122:123]
	v_mad_i64_i32 v[38:39], s[22:23], v32, s29, v[120:121]
	v_or_b32_e32 v33, 32, v32
	v_add_co_u32_e32 v40, vcc, 0x80000, v36
	global_load_dwordx4 v[80:83], v[38:39], off
	global_load_dwordx4 v[84:87], v[36:37], off
	v_mad_i64_i32 v[38:39], s[22:23], v33, s29, v[120:121]
	v_addc_co_u32_e32 v41, vcc, 0, v37, vcc
	global_load_dwordx4 v[88:91], v[38:39], off
	global_load_dwordx4 v[92:95], v[40:41], off
	v_or_b32_e32 v33, 64, v32
	v_add_co_u32_e32 v40, vcc, 0x100000, v36
	v_mad_i64_i32 v[38:39], s[22:23], v33, s29, v[120:121]
	s_nop 0
	v_addc_co_u32_e32 v41, vcc, 0, v37, vcc
	v_or_b32_e32 v33, 0x60, v32
	global_load_dwordx4 v[96:99], v[38:39], off
	global_load_dwordx4 v[100:103], v[40:41], off
	v_mad_i64_i32 v[38:39], s[22:23], v33, s29, v[120:121]
	v_add_co_u32_e32 v36, vcc, 0x180000, v36
	s_nop 1
	v_addc_co_u32_e32 v37, vcc, 0, v37, vcc
	global_load_dwordx4 v[104:107], v[38:39], off
	global_load_dwordx4 v[108:111], v[36:37], off
	s_and_saveexec_b64 s[22:23], s[6:7]
	s_cbranch_execz .LBB0_180
	v_or_b32_e32 v32, v32, v131
	v_ashrrev_i32_e32 v33, 31, v32
	v_lshl_add_u64 v[32:33], v[32:33], 2, s[20:21]
	global_load_dword v234, v[32:33], off
	v_lshl_add_u32 v33, v34, 2, v132
	ds_read_b32 v235, v33 offset:8

; DEV void attn_unit(const Params& P, int b, int qb, int h) {
;     ...
;     const int t = 2 * t2 + sub;
;     const bool active = (t2 < NT2) && (t >= t_start64) && !(t == 2 * qb + 1 && wq < 2);
;     if (active) {
;       f32x16 s0, s1;
; #pragma unroll
;       for (int rq = 0; rq < 4; ++rq) {
;         const f32x4 b0 = *(const f32x4*)(smem + st + AT_BIAS + (64 * sub + 8 * rq + 4 * hi) * 4);
;         const f32x4 b1 = *(const f32x4*)(smem + st + AT_BIAS + (64 * sub + 32 + 8 * rq + 4 * hi) * 4);
; #pragma unroll
;         for (int e = 0; e < 4; ++e) { s0[4 * rq + e] = b0[e]; s1[4 * rq + e] = b1[e]; }
;       }
; #pragma unroll
;       for (int d0 = 0; d0 < 4; ++d0) {
;         const bf16x8 k0 = *(const bf16x8*)(smem + st + AT_K + (64 * sub + l32) * LROW + d0 * 32 + hi * 16);
;         const bf16x8 k1 = *(const bf16x8*)(smem + st + AT_K + (64 * sub + 32 + l32) * LROW + d0 * 32 + hi * 16);
;         s0 = __builtin_amdgcn_mfma_f32_32x32x16_bf16(k0, qf[d0], s0, 0, 0, 0);
;         s1 = __builtin_amdgcn_mfma_f32_32x32x16_bf16(k1, qf[d0], s1, 0, 0, 0);
;       }
;       if (t >= 2 * qb) {
;         const int kb = 64 * (t - 2 * qb), qrel = 32 * wq + l32;
; #pragma unroll
;         for (int r = 0; r < 16; ++r) {
;           const int kv = kb + crow(r, hi);
;           if (kv > qrel) s0[r] = -INFINITY;
;           if (kv + 32 > qrel) s1[r] = -INFINITY;
;         }
.LBB0_184:
	v_or_b32_e32 v126, s44, v145
	v_cmp_ge_i32_e32 vcc, v126, v135
	s_and_b64 s[24:25], s[12:13], vcc
	v_cmp_ne_u32_e32 vcc, s42, v126
	s_or_b64 s[26:27], vcc, s[8:9]
	s_and_b64 s[26:27], s[24:25], s[26:27]
	s_and_saveexec_b64 s[24:25], s[26:27]
	s_cbranch_execz .LBB0_183
	v_lshl_or_b32 v32, s44, 6, v133
	v_mad_u32_u24 v152, v32, s31, v146
	v_lshl_add_u32 v44, s44, 8, v146
	ds_read_b128 v[32:35], v152
	ds_read_b128 v[48:51], v44 offset:35840
	ds_read_b128 v[52:55], v44 offset:35872
	ds_read_b128 v[56:59], v44 offset:35904
	ds_read_b128 v[60:63], v44 offset:35936
	ds_read_b128 v[148:151], v152 offset:4608
	ds_read_b128 v[158:161], v152 offset:32
	v_cmp_le_i32_e32 vcc, s2, v126
	s_waitcnt lgkmcnt(2)
	v_mfma_f32_32x32x16_bf16 v[48:63], v[32:35], v[64:67], v[48:63]
	ds_read_b128 v[32:35], v44 offset:35968
	ds_read_b128 v[36:39], v44 offset:36000
	ds_read_b128 v[40:43], v44 offset:36032
	ds_read_b128 v[44:47], v44 offset:36064
	ds_read_b128 v[162:165], v152 offset:4640
	s_waitcnt lgkmcnt(1)
	v_mfma_f32_32x32x16_bf16 v[32:47], v[148:151], v[64:67], v[32:47]
	v_mfma_f32_32x32x16_bf16 v[48:63], v[158:161], v[68:71], v[48:63]
	ds_read_b128 v[148:151], v152 offset:64
	ds_read_b128 v[158:161], v152 offset:96
	s_waitcnt lgkmcnt(2)
	v_mfma_f32_32x32x16_bf16 v[32:47], v[162:165], v[68:71], v[32:47]
	s_waitcnt lgkmcnt(1)
	v_mfma_f32_32x32x16_bf16 v[48:63], v[148:151], v[72:75], v[48:63]
	ds_read_b128 v[148:151], v152 offset:4672
	ds_read_b128 v[162:165], v152 offset:4704
	s_waitcnt lgkmcnt(1)
	v_mfma_f32_32x32x16_bf16 v[32:47], v[148:151], v[72:75], v[32:47]
	v_mfma_f32_32x32x16_bf16 v[48:63], v[158:161], v[76:79], v[48:63]
	s_waitcnt lgkmcnt(0)
	v_mfma_f32_32x32x16_bf16 v[32:47], v[162:165], v[76:79], v[32:47]
	s_and_saveexec_b64 s[26:27], vcc
	s_cbranch_execz .LBB0_187
	v_subrev_u32_e32 v126, s2, v126
	v_lshl_or_b32 v126, v126, 6, v141
	v_or_b32_e32 v148, 32, v126
	v_cmp_le_u32_e32 vcc, v148, v140
	v_or_b32_e32 v148, 33, v126
	s_nop 4
	v_cndmask_b32_e32 v32, v128, v32, vcc
	v_cmp_lt_u32_e32 vcc, v126, v140
	s_nop 1
	v_cndmask_b32_e32 v49, v128, v49, vcc
	v_cmp_le_u32_e32 vcc, v126, v140
	s_nop 1
	v_cndmask_b32_e32 v48, v128, v48, vcc
	v_cmp_le_u32_e32 vcc, v148, v140
	v_or_b32_e32 v148, 2, v126
	s_nop 0
	v_cndmask_b32_e32 v33, v128, v33, vcc
	v_cmp_le_u32_e32 vcc, v148, v140
	v_or_b32_e32 v148, 34, v126
	s_nop 0
	v_cndmask_b32_e32 v50, v128, v50, vcc
	v_cmp_le_u32_e32 vcc, v148, v140
	v_or_b32_e32 v148, 3, v126
	s_nop 0
	v_cndmask_b32_e32 v34, v128, v34, vcc
	v_cmp_le_u32_e32 vcc, v148, v140
	v_or_b32_e32 v148, 35, v126
	s_nop 0
	v_cndmask_b32_e32 v51, v128, v51, vcc
	v_cmp_le_u32_e32 vcc, v148, v140
	v_or_b32_e32 v148, 8, v126
	s_nop 0
	v_cndmask_b32_e32 v35, v128, v35, vcc
	v_cmp_le_u32_e32 vcc, v148, v140
	v_or_b32_e32 v148, 40, v126
	s_nop 0
	v_cndmask_b32_e32 v52, v128, v52, vcc
	v_cmp_le_u32_e32 vcc, v148, v140
	v_or_b32_e32 v148, 9, v126
	s_nop 0
	v_cndmask_b32_e32 v36, v128, v36, vcc
	v_cmp_le_u32_e32 vcc, v148, v140
	v_or_b32_e32 v148, 41, v126
	s_nop 0
	v_cndmask_b32_e32 v53, v128, v53, vcc
	v_cmp_le_u32_e32 vcc, v148, v140
	v_or_b32_e32 v148, 10, v126
	s_nop 0
	v_cndmask_b32_e32 v37, v128, v37, vcc
	v_cmp_le_u32_e32 vcc, v148, v140
	v_or_b32_e32 v148, 42, v126
	s_nop 0
	v_cndmask_b32_e32 v54, v128, v54, vcc
	v_cmp_le_u32_e32 vcc, v148, v140
	v_or_b32_e32 v148, 11, v126
	s_nop 0
	v_cndmask_b32_e32 v38, v128, v38, vcc
	v_cmp_le_u32_e32 vcc, v148, v140
	v_or_b32_e32 v148, 43, v126
	s_nop 0
	v_cndmask_b32_e32 v55, v128, v55, vcc
	v_cmp_le_u32_e32 vcc, v148, v140
	v_or_b32_e32 v148, 16, v126
	s_nop 0
	v_cndmask_b32_e32 v39, v128, v39, vcc
	v_cmp_le_u32_e32 vcc, v148, v140
	v_or_b32_e32 v148, 48, v126
	s_nop 0
	v_cndmask_b32_e32 v56, v128, v56, vcc
	v_cmp_le_u32_e32 vcc, v148, v140
	v_or_b32_e32 v148, 17, v126
	s_nop 0
	v_cndmask_b32_e32 v40, v128, v40, vcc
	v_cmp_le_u32_e32 vcc, v148, v140
	v_or_b32_e32 v148, 49, v126
	s_nop 0
	v_cndmask_b32_e32 v57, v128, v57, vcc
	v_cmp_le_u32_e32 vcc, v148, v140
	v_or_b32_e32 v148, 18, v126
	s_nop 0
	v_cndmask_b32_e32 v41, v128, v41, vcc
	v_cmp_le_u32_e32 vcc, v148, v140
	v_or_b32_e32 v148, 50, v126
	s_nop 0
	v_cndmask_b32_e32 v58, v128, v58, vcc
	v_cmp_le_u32_e32 vcc, v148, v140
	v_or_b32_e32 v148, 19, v126
	s_nop 0
	v_cndmask_b32_e32 v42, v128, v42, vcc
	v_cmp_le_u32_e32 vcc, v148, v140
	v_or_b32_e32 v148, 51, v126
	s_nop 0
	v_cndmask_b32_e32 v59, v128, v59, vcc
	v_cmp_le_u32_e32 vcc, v148, v140
	v_or_b32_e32 v148, 24, v126
	s_nop 0
	v_cndmask_b32_e32 v43, v128, v43, vcc
	v_cmp_le_u32_e32 vcc, v148, v140
	v_or_b32_e32 v148, 56, v126
	s_nop 0
	v_cndmask_b32_e32 v60, v128, v60, vcc
	v_cmp_le_u32_e32 vcc, v148, v140
	v_or_b32_e32 v148, 25, v126
	s_nop 0
	v_cndmask_b32_e32 v44, v128, v44, vcc
	v_cmp_le_u32_e32 vcc, v148, v140
	v_or_b32_e32 v148, 57, v126
	s_nop 0
	v_cndmask_b32_e32 v61, v128, v61, vcc
	v_cmp_le_u32_e32 vcc, v148, v140
	v_or_b32_e32 v148, 26, v126
	s_nop 0
	v_cndmask_b32_e32 v45, v128, v45, vcc
	v_cmp_le_u32_e32 vcc, v148, v140
	v_or_b32_e32 v148, 58, v126
	s_nop 0
	v_cndmask_b32_e32 v62, v128, v62, vcc
	v_cmp_le_u32_e32 vcc, v148, v140
	v_or_b32_e32 v148, 27, v126
	v_or_b32_e32 v126, 59, v126
	v_cndmask_b32_e32 v46, v128, v46, vcc
	v_cmp_le_u32_e32 vcc, v148, v140
	s_nop 1
	v_cndmask_b32_e32 v63, v128, v63, vcc
	v_cmp_le_u32_e32 vcc, v126, v140
	s_nop 1
	v_cndmask_b32_e32 v47, v128, v47, vcc

; #define AT_STORE(st) do { \
;     _Pragma("unroll") for (int i_ = 0; i_ < 4; ++i_) { *(u32x4*)(smem + (st) + AT_K + sk_ + 32 * i_ * LROW) = rk[i_]; *(u32x4*)(smem + (st) + AT_V + sv_ + 16 * i_ * VROW) = rv[i_]; } \
;     if (gt < 128) *(float*)(smem + (st) + AT_BIAS + gt * 4) = rbias; } while (0)
; DEV void attn_unit(const Params& P, int b, int qb, int h) {
;     ...
;     if (more) AT_STORE(gbase + ((it + 1) & 1) * AT_STG);
.LBB0_189:
	s_and_saveexec_b64 s[12:13], s[10:11]
	s_cbranch_execz .LBB0_176
	s_andn2_b32 s10, 1, s43
	s_mul_i32 s10, s10, 0x8e00
	v_add_u32_e32 v32, s10, v142
	v_add_u32_e32 v33, v32, v136
	v_add_u32_e32 v34, v32, v137
	s_waitcnt vmcnt(7)
	ds_write_b128 v33, v[80:83]
	s_waitcnt vmcnt(6)
	ds_write_b128 v34, v[84:87] offset:18432
	s_waitcnt vmcnt(5)
	ds_write_b128 v33, v[88:91] offset:4608
	s_waitcnt vmcnt(4)
	ds_write_b128 v34, v[92:95] offset:22784
	s_waitcnt vmcnt(3)
	ds_write_b128 v33, v[96:99] offset:9216
	s_waitcnt vmcnt(2)
	ds_write_b128 v34, v[100:103] offset:27136
	s_waitcnt vmcnt(1)
	ds_write_b128 v33, v[104:107] offset:13824
	s_waitcnt vmcnt(0)
	ds_write_b128 v34, v[108:111] offset:31488
	s_and_b64 exec, exec, s[6:7]
	s_cbranch_execz .LBB0_176
	v_add_u32_e32 v32, v32, v143
	v_sub_f32_e32 v234, v134, v234
	v_add_f32_e32 v234, v234, v235
	v_mul_f32_e32 v139, 0x3fb8aa3b, v234
	ds_write_b32 v32, v139 offset:35840
	s_branch .LBB0_176
